# NSA selected-block branch: hand-written in-place fast path for past blocks (no register copy-in/out, direct MFMA-layout fragment reads)
# speedup vs baseline: 1.0203x; 1.0203x over previous
; #define LAS __attribute__((address_space(3)))
; template <int MODE> __device__ __forceinline__ void tile_softmax(f32x4 (&S)[4], bool rowv, int kfirst, int klo, unsigned kspan, float& l) {
;     ...
;         for (int j = 0; j < 4; ++j) { float e = __builtin_amdgcn_exp2f(S[st][j]);
;             if (MODE == 1) e = rowv ? e : 0.f;
;             if (MODE == 2) e = ((unsigned)(kfirst + st * 16 + j - klo) <= kspan) ? e : 0.f;
;             S[st][j] = e; ps += e; }
;     l += ps;
; }
; __device__ __forceinline__ void nsa_loadk(const LAS unsigned char* kbuf, int offk0, int offk1, bf16x8 (&ka)[4], bf16x8 (&kb)[4]) {
; #pragma unroll
;     for (int st = 0; st < 4; ++st) { ka[st] = *(const LAS bf16x8*)(kbuf + offk0 + st * 2048); kb[st] = *(const LAS bf16x8*)(kbuf + offk1 + st * 2048); }
; }
; __device__ __forceinline__ void nsa_loadv(const LAS unsigned char* vbuf, int offv00, int offv01, int offv10, int offv11, u32x4 (&vf)[2][4]) {
; #pragma unroll
;     for (int dt = 0; dt < 4; ++dt) { const u32x2 lo0 = *(const LAS u32x2*)(vbuf + offv00 + dt * 2048), hi0 = *(const LAS u32x2*)(vbuf + offv01 + dt * 2048), lo1 = *(const LAS u32x2*)(vbuf + offv10 + dt * 2048), hi1 = *(const LAS u32x2*)(vbuf + offv11 + dt * 2048);
;         vf[0][dt].x = lo0.x; vf[0][dt].y = lo0.y; vf[0][dt].z = hi0.x; vf[0][dt].w = hi0.y; vf[1][dt].x = lo1.x; vf[1][dt].y = lo1.y; vf[1][dt].z = hi1.x; vf[1][dt].w = hi1.y; }
; }
; __device__ __forceinline__ void nsa_scores(const bf16x8 (&ka)[4], const bf16x8 (&kb)[4], bf16x8 q0, bf16x8 q1, f32x4 (&S)[4]) {
;     const f32x4 zero4 = {0.f, 0.f, 0.f, 0.f};
; #pragma unroll
; __device__ __forceinline__ void nsa_wg_task(bf16_t* zb, const bf16_t* kcb, const bf16_t* vctb, const bf16_t* vst, const bf16_t* vwt, int g, int T0, float* accb, LAS unsigned char* lds, int wave, int lane, int tid) {
;     ...
;                 for (int r = 0; r < 2; ++r) if (any[r]) { nsa_scores(ka, kb, q0[r], q1[r], S);
;                     if (kb0 + 63 <= t0[r]) { if (all4[r]) tile_softmax<0>(S, true, 0, 0, 0u, l[r]); else tile_softmax<1>(S, mine[r], 0, 0, 0u, l[r]); }
;                     else tile_softmax<2>(S, false, kb0 + 4 * fq, mine[r] ? 0 : 0x40000000, (unsigned)t[r], l[r]);
;                     nsa_pack(S, pf[r]); }
;                 nsa_loadv(vbuf, offv00, offv01, offv10, offv11, vf);
; #pragma unroll
;                 for (int r = 0; r < 2; ++r) if (any[r]) nsa_pv(vf, pf[r], O[r]); }
.Lsel_fast:
	v_add_u32_e32 v124, s45, v195
	v_add_u32_e32 v125, s45, v196
	ds_read_b128 v[132:135], v124
	ds_read_b128 v[136:139], v124 offset:2048
	ds_read_b128 v[140:143], v124 offset:4096
	ds_read_b128 v[144:147], v124 offset:6144
	ds_read_b128 v[148:151], v125
	ds_read_b128 v[152:155], v125 offset:2048
	ds_read_b128 v[116:119], v125 offset:4096
	ds_read_b128 v[120:123], v125 offset:6144
	v_add_u32_e32 v126, s45, v197
	v_add_u32_e32 v127, s45, v198
	v_add_u32_e32 v128, s45, v199
	v_add_u32_e32 v129, s45, v206
	s_waitcnt lgkmcnt(0)
	s_and_b64 vcc, exec, s[56:57]
	s_cbranch_vccz .Lsf_qk_done0
	v_mfma_f32_16x16x32_bf16 v[16:19], v[132:135], v[60:63], 0
	v_mfma_f32_16x16x32_bf16 v[20:23], v[136:139], v[60:63], 0
	v_mfma_f32_16x16x32_bf16 v[24:27], v[140:143], v[60:63], 0
	v_mfma_f32_16x16x32_bf16 v[28:31], v[144:147], v[60:63], 0
	v_mfma_f32_16x16x32_bf16 v[16:19], v[148:151], v[72:75], v[16:19]
	v_mfma_f32_16x16x32_bf16 v[20:23], v[152:155], v[72:75], v[20:23]
	v_mfma_f32_16x16x32_bf16 v[24:27], v[116:119], v[72:75], v[24:27]
	v_mfma_f32_16x16x32_bf16 v[28:31], v[120:123], v[72:75], v[28:31]
.Lsf_qk_done0:
	s_and_b64 vcc, exec, s[28:29]
	s_cbranch_vccz .Lsf_qk_done1
	v_mfma_f32_16x16x32_bf16 v[32:35], v[132:135], v[76:79], 0
	v_mfma_f32_16x16x32_bf16 v[36:39], v[136:139], v[76:79], 0
	v_mfma_f32_16x16x32_bf16 v[40:43], v[140:143], v[76:79], 0
	v_mfma_f32_16x16x32_bf16 v[44:47], v[144:147], v[76:79], 0
	v_mfma_f32_16x16x32_bf16 v[32:35], v[148:151], v[80:83], v[32:35]
	v_mfma_f32_16x16x32_bf16 v[36:39], v[152:155], v[80:83], v[36:39]
	v_mfma_f32_16x16x32_bf16 v[40:43], v[116:119], v[80:83], v[40:43]
	v_mfma_f32_16x16x32_bf16 v[44:47], v[120:123], v[80:83], v[44:47]
.Lsf_qk_done1:
	s_nop 3
	ds_read_b64 v[132:133], v126 offset:8192
	ds_read_b64 v[134:135], v127 offset:8192
	ds_read_b64 v[148:149], v128 offset:8192
	ds_read_b64 v[150:151], v129 offset:8192
	ds_read_b64 v[136:137], v126 offset:10240
	ds_read_b64 v[138:139], v127 offset:10240
	ds_read_b64 v[152:153], v128 offset:10240
	ds_read_b64 v[154:155], v129 offset:10240
	ds_read_b64 v[140:141], v126 offset:12288
	ds_read_b64 v[142:143], v127 offset:12288
	ds_read_b64 v[116:117], v128 offset:12288
	ds_read_b64 v[118:119], v129 offset:12288
	ds_read_b64 v[144:145], v126 offset:14336
	ds_read_b64 v[146:147], v127 offset:14336
	ds_read_b64 v[120:121], v128 offset:14336
	ds_read_b64 v[122:123], v129 offset:14336
	s_nop 7
	s_and_b64 vcc, exec, s[56:57]
	s_cbranch_vccz .Lsf_sm_done0
	v_exp_f32_e32 v16, v16
	v_exp_f32_e32 v17, v17
	v_exp_f32_e32 v18, v18
	v_exp_f32_e32 v19, v19
	v_exp_f32_e32 v20, v20
	v_exp_f32_e32 v21, v21
	v_exp_f32_e32 v22, v22
	v_exp_f32_e32 v23, v23
	v_exp_f32_e32 v24, v24
	v_exp_f32_e32 v25, v25
	v_exp_f32_e32 v26, v26
	v_exp_f32_e32 v27, v27
	v_exp_f32_e32 v28, v28
	v_exp_f32_e32 v29, v29
	v_exp_f32_e32 v30, v30
	v_exp_f32_e32 v31, v31
	s_cmp_eq_u64 s[24:25], -1
	s_cbranch_scc1 .Lsf_all0
	v_cndmask_b32_e64 v16, 0, v16, s[24:25]
	v_cndmask_b32_e64 v17, 0, v17, s[24:25]
	v_cndmask_b32_e64 v18, 0, v18, s[24:25]
	v_cndmask_b32_e64 v19, 0, v19, s[24:25]
	v_cndmask_b32_e64 v20, 0, v20, s[24:25]
	v_cndmask_b32_e64 v21, 0, v21, s[24:25]
	v_cndmask_b32_e64 v22, 0, v22, s[24:25]
	v_cndmask_b32_e64 v23, 0, v23, s[24:25]
	v_cndmask_b32_e64 v24, 0, v24, s[24:25]
	v_cndmask_b32_e64 v25, 0, v25, s[24:25]
	v_cndmask_b32_e64 v26, 0, v26, s[24:25]
	v_cndmask_b32_e64 v27, 0, v27, s[24:25]
	v_cndmask_b32_e64 v28, 0, v28, s[24:25]
	v_cndmask_b32_e64 v29, 0, v29, s[24:25]
	v_cndmask_b32_e64 v30, 0, v30, s[24:25]
	v_cndmask_b32_e64 v31, 0, v31, s[24:25]
; __device__ __forceinline__ unsigned cvt_pk_bf16(float lo, float hi) { unsigned r; asm volatile("v_cvt_pk_bf16_f32 %0, %1, %2" : "=v"(r) : "v"(lo), "v"(hi)); return r; }
; __device__ __forceinline__ f32x4 mfma16(bf16x8 a, bf16x8 b, f32x4 c) { return __builtin_amdgcn_mfma_f32_16x16x32_bf16(a, b, c, 0, 0, 0); }
; template <int MODE> __device__ __forceinline__ void tile_softmax(f32x4 (&S)[4], bool rowv, int kfirst, int klo, unsigned kspan, float& l) {
;     ...
;         for (int j = 0; j < 4; ++j) { float e = __builtin_amdgcn_exp2f(S[st][j]);
;             if (MODE == 1) e = rowv ? e : 0.f;
;             if (MODE == 2) e = ((unsigned)(kfirst + st * 16 + j - klo) <= kspan) ? e : 0.f;
;             S[st][j] = e; ps += e; }
;     l += ps;
; __device__ __forceinline__ void nsa_pack(const f32x4 (&P)[4], u32x4 (&pf)[2]) {
; #pragma unroll
;     for (int hf = 0; hf < 2; ++hf) { pf[hf].x = cvt_pk_bf16(P[2 * hf][0], P[2 * hf][1]); pf[hf].y = cvt_pk_bf16(P[2 * hf][2], P[2 * hf][3]); pf[hf].z = cvt_pk_bf16(P[2 * hf + 1][0], P[2 * hf + 1][1]); pf[hf].w = cvt_pk_bf16(P[2 * hf + 1][2], P[2 * hf + 1][3]); }
; }
; __device__ __forceinline__ void nsa_pv(const u32x4 (&vf)[2][4], const u32x4 (&pf)[2], f32x4 (&O)[4]) {
; #pragma unroll
;     for (int hf = 0; hf < 2; ++hf)
; #pragma unroll
;         for (int dt = 0; dt < 4; ++dt) O[dt] = mfma16(__builtin_bit_cast(bf16x8, vf[hf][dt]), __builtin_bit_cast(bf16x8, pf[hf]), O[dt]);
; }
.Lsf_all0:
	s_nop 0
	v_add_f32_e32 v124, 0, v16
	v_add_f32_e32 v124, v124, v17
	v_add_f32_e32 v124, v124, v18
	v_add_f32_e32 v124, v124, v19
	v_add_f32_e32 v124, v124, v20
	v_add_f32_e32 v124, v124, v21
	v_add_f32_e32 v124, v124, v22
	v_add_f32_e32 v124, v124, v23
	v_add_f32_e32 v124, v124, v24
	v_add_f32_e32 v124, v124, v25
	v_add_f32_e32 v124, v124, v26
	v_add_f32_e32 v124, v124, v27
	v_add_f32_e32 v124, v124, v28
	v_add_f32_e32 v124, v124, v29
	v_add_f32_e32 v124, v124, v30
	v_add_f32_e32 v124, v124, v31
	v_add_f32_e32 v172, v172, v124
	v_cvt_pk_bf16_f32 v16, v16, v17
	v_cvt_pk_bf16_f32 v17, v18, v19
	v_cvt_pk_bf16_f32 v18, v20, v21
	v_cvt_pk_bf16_f32 v19, v22, v23
	v_cvt_pk_bf16_f32 v20, v24, v25
	v_cvt_pk_bf16_f32 v21, v26, v27
	v_cvt_pk_bf16_f32 v22, v28, v29
	v_cvt_pk_bf16_f32 v23, v30, v31
.Lsf_sm_done0:
	s_and_b64 vcc, exec, s[28:29]
	s_cbranch_vccz .Lsf_sm_done1
	v_exp_f32_e32 v32, v32
	v_exp_f32_e32 v33, v33
	v_exp_f32_e32 v34, v34
	v_exp_f32_e32 v35, v35
	v_exp_f32_e32 v36, v36
	v_exp_f32_e32 v37, v37
	v_exp_f32_e32 v38, v38
	v_exp_f32_e32 v39, v39
	v_exp_f32_e32 v40, v40
	v_exp_f32_e32 v41, v41
	v_exp_f32_e32 v42, v42
	v_exp_f32_e32 v43, v43
	v_exp_f32_e32 v44, v44
	v_exp_f32_e32 v45, v45
	v_exp_f32_e32 v46, v46
	v_exp_f32_e32 v47, v47
	s_cmp_eq_u64 s[22:23], -1
	s_cbranch_scc1 .Lsf_all1
	v_cndmask_b32_e64 v32, 0, v32, s[22:23]
	v_cndmask_b32_e64 v33, 0, v33, s[22:23]
	v_cndmask_b32_e64 v34, 0, v34, s[22:23]
	v_cndmask_b32_e64 v35, 0, v35, s[22:23]
	v_cndmask_b32_e64 v36, 0, v36, s[22:23]
	v_cndmask_b32_e64 v37, 0, v37, s[22:23]
	v_cndmask_b32_e64 v38, 0, v38, s[22:23]
	v_cndmask_b32_e64 v39, 0, v39, s[22:23]
	v_cndmask_b32_e64 v40, 0, v40, s[22:23]
	v_cndmask_b32_e64 v41, 0, v41, s[22:23]
	v_cndmask_b32_e64 v42, 0, v42, s[22:23]
	v_cndmask_b32_e64 v43, 0, v43, s[22:23]
	v_cndmask_b32_e64 v44, 0, v44, s[22:23]
	v_cndmask_b32_e64 v45, 0, v45, s[22:23]
	v_cndmask_b32_e64 v46, 0, v46, s[22:23]
	v_cndmask_b32_e64 v47, 0, v47, s[22:23]
.Lsf_all1:
	s_nop 0
	v_add_f32_e32 v124, 0, v32
	v_add_f32_e32 v124, v124, v33
	v_add_f32_e32 v124, v124, v34
	v_add_f32_e32 v124, v124, v35
	v_add_f32_e32 v124, v124, v36
	v_add_f32_e32 v124, v124, v37
	v_add_f32_e32 v124, v124, v38
	v_add_f32_e32 v124, v124, v39
	v_add_f32_e32 v124, v124, v40
	v_add_f32_e32 v124, v124, v41
	v_add_f32_e32 v124, v124, v42
	v_add_f32_e32 v124, v124, v43
	v_add_f32_e32 v124, v124, v44
	v_add_f32_e32 v124, v124, v45
	v_add_f32_e32 v124, v124, v46
	v_add_f32_e32 v124, v124, v47
	v_add_f32_e32 v173, v173, v124
	v_cvt_pk_bf16_f32 v32, v32, v33
	v_cvt_pk_bf16_f32 v33, v34, v35
	v_cvt_pk_bf16_f32 v34, v36, v37
	v_cvt_pk_bf16_f32 v35, v38, v39
	v_cvt_pk_bf16_f32 v36, v40, v41
	v_cvt_pk_bf16_f32 v37, v42, v43
	v_cvt_pk_bf16_f32 v38, v44, v45
	v_cvt_pk_bf16_f32 v39, v46, v47
.Lsf_sm_done1:
	s_waitcnt lgkmcnt(0)
	s_nop 1
	s_and_b64 vcc, exec, s[56:57]
	s_cbranch_vccz .Lsf_pv_done0
	v_mfma_f32_16x16x32_bf16 v[112:115], v[132:135], v[16:19], v[112:115]
	v_mfma_f32_16x16x32_bf16 v[108:111], v[136:139], v[16:19], v[108:111]
	v_mfma_f32_16x16x32_bf16 v[104:107], v[140:143], v[16:19], v[104:107]
	v_mfma_f32_16x16x32_bf16 v[100:103], v[144:147], v[16:19], v[100:103]
	v_mfma_f32_16x16x32_bf16 v[112:115], v[148:151], v[20:23], v[112:115]
	v_mfma_f32_16x16x32_bf16 v[108:111], v[152:155], v[20:23], v[108:111]
	v_mfma_f32_16x16x32_bf16 v[104:107], v[116:119], v[20:23], v[104:107]
	v_mfma_f32_16x16x32_bf16 v[100:103], v[120:123], v[20:23], v[100:103]
.Lsf_pv_done0:
	s_and_b64 vcc, exec, s[28:29]
	s_cbranch_vccz .Lsf_pv_done1
	v_mfma_f32_16x16x32_bf16 v[96:99], v[132:135], v[32:35], v[96:99]
	v_mfma_f32_16x16x32_bf16 v[92:95], v[136:139], v[32:35], v[92:95]
	v_mfma_f32_16x16x32_bf16 v[88:91], v[140:143], v[32:35], v[88:91]
	v_mfma_f32_16x16x32_bf16 v[84:87], v[144:147], v[32:35], v[84:87]
	v_mfma_f32_16x16x32_bf16 v[96:99], v[148:151], v[36:39], v[96:99]
	v_mfma_f32_16x16x32_bf16 v[92:95], v[152:155], v[36:39], v[92:95]
	v_mfma_f32_16x16x32_bf16 v[88:91], v[116:119], v[36:39], v[88:91]
	v_mfma_f32_16x16x32_bf16 v[84:87], v[120:123], v[36:39], v[84:87]
.Lsf_pv_done1:
	s_nop 7
	s_branch .LBB0_345

; __device__ __forceinline__ void nsa_wg_task(bf16_t* zb, const bf16_t* kcb, const bf16_t* vctb, const bf16_t* vst, const bf16_t* vwt, int g, int T0, float* accb, LAS unsigned char* lds, int wave, int lane, int tid) {
;     ...
;             const int s = i - 2 * nc, kb0 = s * 64;
;             bool any[2], mine[2], all4[2];
;             const unsigned mwd0 = wM[ti * 4 + (s >> 5)], mwd1 = wM[(4 + ti) * 4 + (s >> 5)];
;             nsa_loadk(kbuf, offk0, offk1, ka, kb);
; #pragma unroll
;             for (int r = 0; r < 2; ++r) { const unsigned mwd = r == 0 ? mwd0 : mwd1; mine[r] = ((mwd >> (s & 31)) & 1u) != 0u; const unsigned long long bal = __ballot(mine[r]); any[r] = bal != 0ull && kb0 <= tmax[r]; all4[r] = bal == ~0ull; }
;             if (any[0] || any[1]) {
; #pragma unroll
;                 for (int r = 0; r < 2; ++r) if (any[r]) { nsa_scores(ka, kb, q0[r], q1[r], S);
;                     if (kb0 + 63 <= t0[r]) { if (all4[r]) tile_softmax<0>(S, true, 0, 0, 0u, l[r]); else tile_softmax<1>(S, mine[r], 0, 0, 0u, l[r]); }
;                     else tile_softmax<2>(S, false, kb0 + 4 * fq, mine[r] ? 0 : 0x40000000, (unsigned)t[r], l[r]);
.LBB0_209:
	s_add_i32 s44, s34, s75
	s_cmp_gt_i32 s44, s38
	s_mov_b64 s[20:21], -1
	s_cbranch_scc1 .LBB0_208
	s_add_i32 s2, s34, s1
	s_lshl_b32 s2, s2, 14
	s_add_i32 s45, s2, 0
	s_cmp_ge_i32 s44, s70
	s_cbranch_scc0 .LBB0_334
	s_cmp_ge_i32 s44, s71
	s_cbranch_scc0 .LBB0_260
	s_cmp_gt_i32 s44, s84
	s_cbranch_scc1 .LBB0_240
	s_sub_i32 s2, s44, s71
	s_ashr_i32 s20, s2, 5
	s_waitcnt lgkmcnt(0)
	v_lshl_add_u32 v16, s20, 2, v207
	ds_read2_b32 v[16:17], v16 offset1:16
	s_lshl_b32 s21, 1, s2
	s_lshl_b32 s20, s2, 6
	v_mov_b64_e32 v[32:33], v[84:85]
	v_mov_b64_e32 v[36:37], v[88:89]
	s_waitcnt lgkmcnt(0)
	v_and_b32_e32 v16, s21, v16
	v_cmp_ne_u32_e64 s[24:25], 0, v16
	s_cmp_lg_u64 s[24:25], 0
	s_cselect_b64 s[22:23], -1, 0
	s_cmp_le_i32 s20, s85
	v_and_b32_e32 v17, s21, v17
	s_cselect_b64 s[28:29], -1, 0
	s_and_b64 s[56:57], s[22:23], s[28:29]
	v_cmp_ne_u32_e64 s[22:23], 0, v17
	s_cmp_lg_u64 s[22:23], 0
	s_cselect_b64 s[28:29], -1, 0
	s_cmp_le_i32 s20, s81
	s_cselect_b64 s[94:95], -1, 0
	s_and_b64 s[28:29], s[28:29], s[94:95]
	s_or_b64 s[94:95], s[56:57], s[28:29]
	s_cmp_eq_u32 s2, s61
	s_cbranch_scc1 .Lnsa_sel_noskip
	s_andn2_b64 vcc, exec, s[94:95]
	s_cbranch_vccnz .LBB0_345
	s_branch .Lsel_fast
.Lnsa_sel_noskip:
	v_mov_b64_e32 v[30:31], v[14:15]
	v_mov_b64_e32 v[40:41], v[92:93]
	v_mov_b64_e32 v[44:45], v[96:97]
	v_mov_b64_e32 v[48:49], v[100:101]
	v_mov_b64_e32 v[52:53], v[104:105]
	v_mov_b64_e32 v[118:119], v[110:111]
	v_mov_b64_e32 v[122:123], v[114:115]
	s_andn2_b64 vcc, exec, s[94:95]
	v_mov_b64_e32 v[186:187], v[172:173]
	v_mov_b64_e32 v[28:29], v[12:13]
	v_mov_b64_e32 v[26:27], v[10:11]
	v_mov_b64_e32 v[24:25], v[8:9]
	v_mov_b64_e32 v[22:23], v[6:7]
	v_mov_b64_e32 v[20:21], v[4:5]
	v_mov_b64_e32 v[18:19], v[2:3]
	v_mov_b64_e32 v[16:17], v[0:1]
	v_mov_b64_e32 v[34:35], v[86:87]
	v_mov_b64_e32 v[38:39], v[90:91]
	v_mov_b64_e32 v[42:43], v[94:95]
	v_mov_b64_e32 v[46:47], v[98:99]
	v_mov_b64_e32 v[50:51], v[102:103]
	v_mov_b64_e32 v[54:55], v[106:107]
	v_mov_b64_e32 v[116:117], v[108:109]
	v_mov_b64_e32 v[120:121], v[112:113]
	s_cbranch_vccnz .LBB0_237
	v_add_u32_e32 v16, s45, v195
	v_add_u32_e32 v17, s45, v196
	ds_read_b128 v[116:119], v16
	ds_read_b128 v[120:123], v16 offset:2048
	ds_read_b128 v[46:49], v17
	ds_read_b128 v[50:53], v17 offset:2048
	ds_read_b128 v[132:135], v16 offset:4096
	ds_read_b128 v[136:139], v16 offset:6144
	ds_read_b128 v[124:127], v17 offset:4096
	ds_read_b128 v[128:131], v17 offset:6144
	v_cndmask_b32_e64 v16, 0, 1, s[56:57]
	s_or_b32 s94, s20, 63
	v_add_u32_e32 v65, s20, v166
	v_cmp_ne_u32_e64 s[20:21], 1, v16
	v_mov_b64_e32 v[30:31], v[14:15]
	s_andn2_b64 vcc, exec, s[56:57]
	v_mov_b64_e32 v[28:29], v[12:13]
	v_mov_b64_e32 v[26:27], v[10:11]
	v_mov_b64_e32 v[24:25], v[8:9]
	v_mov_b64_e32 v[22:23], v[6:7]
	v_mov_b64_e32 v[20:21], v[4:5]
	v_mov_b64_e32 v[18:19], v[2:3]
	v_mov_b64_e32 v[16:17], v[0:1]
	v_mov_b32_e32 v186, v172
	s_cbranch_vccnz .LBB0_223
	s_waitcnt lgkmcnt(0)
	v_mfma_f32_16x16x32_bf16 v[16:19], v[116:119], v[60:63], 0
	s_mov_b64 s[56:57], -1
	s_cmp_gt_i32 s94, s88
	v_mfma_f32_16x16x32_bf16 v[20:23], v[120:123], v[60:63], 0
	v_mfma_f32_16x16x32_bf16 v[24:27], v[132:135], v[60:63], 0
	v_mfma_f32_16x16x32_bf16 v[28:31], v[136:139], v[60:63], 0
	v_mfma_f32_16x16x32_bf16 v[152:155], v[46:49], v[72:75], v[16:19]
	v_mfma_f32_16x16x32_bf16 v[148:151], v[50:53], v[72:75], v[20:23]
	v_mfma_f32_16x16x32_bf16 v[144:147], v[124:127], v[72:75], v[24:27]
	s_nop 5
	v_exp_f32_e32 v16, v152
	v_mfma_f32_16x16x32_bf16 v[140:143], v[128:131], v[72:75], v[28:31]
	s_cbranch_scc1 .LBB0_220
	s_cmp_lg_u64 s[24:25], -1
	s_cbranch_scc0 .LBB0_346
	v_exp_f32_e32 v17, v153
	v_cndmask_b32_e64 v30, 0, v16, s[24:25]
	v_exp_f32_e32 v18, v154
	v_add_f32_e32 v19, 0, v30
	v_cndmask_b32_e64 v31, 0, v17, s[24:25]
	v_add_f32_e32 v17, v31, v19
	v_exp_f32_e32 v19, v155
	v_cndmask_b32_e64 v32, 0, v18, s[24:25]
	v_exp_f32_e32 v18, v148
	v_add_f32_e32 v17, v32, v17
	v_cndmask_b32_e64 v33, 0, v19, s[24:25]
	v_exp_f32_e32 v19, v149
	v_cndmask_b32_e64 v34, 0, v18, s[24:25]
	v_exp_f32_e32 v18, v150
	v_add_f32_e32 v17, v33, v17
	v_cndmask_b32_e64 v35, 0, v19, s[24:25]
	v_exp_f32_e32 v19, v151
	v_cndmask_b32_e64 v36, 0, v18, s[24:25]
	v_exp_f32_e32 v18, v144
	v_add_f32_e32 v17, v34, v17
	v_cndmask_b32_e64 v37, 0, v19, s[24:25]
	v_exp_f32_e32 v19, v145
	v_cndmask_b32_e64 v38, 0, v18, s[24:25]
	v_exp_f32_e32 v18, v146
	v_add_f32_e32 v17, v35, v17
	v_cndmask_b32_e64 v39, 0, v19, s[24:25]
	v_exp_f32_e32 v19, v147
	v_cndmask_b32_e64 v40, 0, v18, s[24:25]
	v_exp_f32_e32 v18, v140
	v_add_f32_e32 v17, v36, v17
	v_cndmask_b32_e64 v41, 0, v19, s[24:25]
	v_exp_f32_e32 v19, v141
	v_add_f32_e32 v17, v37, v17
	v_add_f32_e32 v17, v38, v17
	v_add_f32_e32 v17, v39, v17
	v_cndmask_b32_e64 v42, 0, v18, s[24:25]
	v_exp_f32_e32 v18, v142
	v_add_f32_e32 v17, v40, v17
	v_cndmask_b32_e64 v43, 0, v19, s[24:25]
	v_exp_f32_e32 v19, v143
	v_add_f32_e32 v17, v41, v17
	v_add_f32_e32 v17, v42, v17
	v_add_f32_e32 v17, v43, v17
	v_cndmask_b32_e64 v44, 0, v18, s[24:25]
	v_add_f32_e32 v17, v44, v17
	v_cndmask_b32_e64 v45, 0, v19, s[24:25]
	v_add_f32_e32 v54, v45, v17
	s_cbranch_execnz .LBB0_219
